# gemm3 residual epilogue: gate and x loads issued up front with counted waits
# baseline (speedup 1.0000x reference)
.LBB0_1054:
	v_add_u32_e32 v99, v125, v128
	ds_read_b128 v[66:69], v99 offset:16384
	ds_read_b128 v[100:103], v99 offset:18432
	ds_read_b128 v[104:107], v99 offset:20480
	ds_read_b128 v[108:111], v99 offset:22528
	v_add_u32_e32 v99, v126, v128
	ds_read_b128 v[130:133], v99 offset:49152
	ds_read_b128 v[134:137], v99 offset:51200
	ds_read_b128 v[138:141], v99 offset:53248
	ds_read_b128 v[142:145], v99 offset:55296
	v_add_u32_e32 v99, v125, v129
	ds_read_b128 v[214:217], v99 offset:16384
	ds_read_b128 v[218:221], v99 offset:18432
	ds_read_b128 v[222:225], v99 offset:20480
	ds_read_b128 v[226:229], v99 offset:22528
	v_add_u32_e32 v99, v126, v129
	ds_read_b128 v[230:233], v99 offset:49152
	ds_read_b128 v[234:237], v99 offset:51200
	ds_read_b128 v[238:241], v99 offset:53248
	s_setprio 1
	s_waitcnt lgkmcnt(7)
	ds_read_b128 v[242:245], v99 offset:55296
	v_mfma_f32_16x16x32_bf16 v[2:5], v[130:133], v[66:69], v[2:5]
	v_mfma_f32_16x16x32_bf16 v[6:9], v[134:137], v[66:69], v[6:9]
	v_mfma_f32_16x16x32_bf16 v[10:13], v[138:141], v[66:69], v[10:13]
	v_mfma_f32_16x16x32_bf16 v[14:17], v[142:145], v[66:69], v[14:17]
	v_mfma_f32_16x16x32_bf16 v[18:21], v[130:133], v[100:103], v[18:21]
	v_mfma_f32_16x16x32_bf16 v[22:25], v[134:137], v[100:103], v[22:25]
	v_mfma_f32_16x16x32_bf16 v[26:29], v[138:141], v[100:103], v[26:29]
	v_mfma_f32_16x16x32_bf16 v[30:33], v[142:145], v[100:103], v[30:33]
	v_mfma_f32_16x16x32_bf16 v[34:37], v[130:133], v[104:107], v[34:37]
	v_mfma_f32_16x16x32_bf16 v[38:41], v[134:137], v[104:107], v[38:41]
	v_mfma_f32_16x16x32_bf16 v[42:45], v[138:141], v[104:107], v[42:45]
	v_mfma_f32_16x16x32_bf16 v[46:49], v[142:145], v[104:107], v[46:49]
	v_mfma_f32_16x16x32_bf16 v[50:53], v[130:133], v[108:111], v[50:53]
	v_mfma_f32_16x16x32_bf16 v[54:57], v[134:137], v[108:111], v[54:57]
	v_mfma_f32_16x16x32_bf16 v[100:103], v[138:141], v[108:111], v[58:61]
	v_mfma_f32_16x16x32_bf16 v[104:107], v[142:145], v[108:111], v[62:65]
	s_waitcnt lgkmcnt(0)
	v_mfma_f32_16x16x32_bf16 v[146:149], v[230:233], v[214:217], v[2:5]
	v_mfma_f32_16x16x32_bf16 v[150:153], v[234:237], v[214:217], v[6:9]
	v_mfma_f32_16x16x32_bf16 v[154:157], v[238:241], v[214:217], v[10:13]
	v_mfma_f32_16x16x32_bf16 v[158:161], v[242:245], v[214:217], v[14:17]
	v_mfma_f32_16x16x32_bf16 v[162:165], v[230:233], v[218:221], v[18:21]
	v_mfma_f32_16x16x32_bf16 v[166:169], v[234:237], v[218:221], v[22:25]
	v_mfma_f32_16x16x32_bf16 v[176:179], v[238:241], v[218:221], v[26:29]
	v_mfma_f32_16x16x32_bf16 v[180:183], v[242:245], v[218:221], v[30:33]
	v_mfma_f32_16x16x32_bf16 v[184:187], v[230:233], v[222:225], v[34:37]
	v_mfma_f32_16x16x32_bf16 v[210:213], v[234:237], v[222:225], v[38:41]
	v_mfma_f32_16x16x32_bf16 v[58:61], v[238:241], v[222:225], v[42:45]
	v_mfma_f32_16x16x32_bf16 v[66:69], v[242:245], v[222:225], v[46:49]
	v_mfma_f32_16x16x32_bf16 v[62:65], v[230:233], v[226:229], v[50:53]
	v_mfma_f32_16x16x32_bf16 v[54:57], v[234:237], v[226:229], v[54:57]
	v_mfma_f32_16x16x32_bf16 v[46:49], v[238:241], v[226:229], v[100:103]
	v_mfma_f32_16x16x32_bf16 v[2:5], v[242:245], v[226:229], v[104:107]
	s_setprio 0
	s_min_i32 s0, s19, 0x4000
	s_ashr_i32 s0, s0, 11
	s_add_i32 s0, s0, s24
	s_mul_hi_i32 s1, s0, 0x6000
	s_mulk_i32 s0, 0x6000
	v_add_u32_e32 v8, s19, v127
	s_add_u32 s22, s94, s0
	v_ashrrev_i32_e32 v9, 31, v8
	s_addc_u32 s27, s95, s1
	s_lshl_b64 s[0:1], s[38:39], 2
	v_lshlrev_b64 v[8:9], 12, v[8:9]
	s_add_u32 s26, s22, s0
	v_lshl_add_u64 v[10:11], s[94:95], 0, v[8:9]
	v_lshl_add_u64 v[8:9], s[92:93], 0, v[8:9]
	s_addc_u32 s27, s27, s1
	v_lshl_add_u64 v[10:11], v[10:11], 0, s[0:1]
	v_lshl_add_u64 v[8:9], v[8:9], 0, s[0:1]
	v_readlane_b32 s0, v253, 38
	v_lshl_add_u64 v[6:7], s[26:27], 0, v[0:1]
	v_mov_b32_e32 v99, v1
	v_lshl_add_u64 v[10:11], v[10:11], 0, v[0:1]
	v_lshl_add_u64 v[8:9], v[8:9], 0, v[0:1]
	v_readlane_b32 s1, v253, 39
	v_lshl_add_u64 v[6:7], v[6:7], 0, v[98:99]
	s_mov_b64 s[26:27], 0x13585000
	v_cndmask_b32_e64 v9, v11, v9, s[0:1]
	v_cndmask_b32_e64 v8, v10, v8, s[0:1]
	s_mov_b32 s0, 0x13585000
	v_lshl_add_u64 v[18:19], v[6:7], 0, s[26:27]
	v_add_co_u32_e32 v6, vcc, s0, v6
	v_lshl_add_u64 v[102:103], v[10:11], 0, v[98:99]
	s_nop 0
	v_addc_co_u32_e32 v7, vcc, 0, v7, vcc
	s_mov_b32 s0, 0x10000
	v_add_co_u32_e32 v38, vcc, s0, v102
	s_mov_b32 s1, 0x20000
	s_nop 0
	v_addc_co_u32_e32 v39, vcc, 0, v103, vcc
	v_add_co_u32_e32 v138, vcc, s1, v102
	v_lshl_add_u64 v[100:101], v[8:9], 0, v[98:99]
	s_nop 0
	v_addc_co_u32_e32 v139, vcc, 0, v103, vcc
	global_load_dwordx4 v[104:107], v[18:19], off
	global_load_dwordx4 v[108:111], v[18:19], off offset:64
	global_load_dwordx4 v[130:133], v[18:19], off offset:128
	global_load_dwordx4 v[26:29], v[18:19], off offset:192
	v_add_co_u32_e32 v238, vcc, 0x30000, v102
	s_nop 1
	v_addc_co_u32_e32 v239, vcc, 0, v103, vcc
	global_load_dwordx4 v[6:9], v[102:103], off
	global_load_dwordx4 v[10:13], v[102:103], off offset:64
	global_load_dwordx4 v[14:17], v[102:103], off offset:128
	global_load_dwordx4 v[18:21], v[102:103], off offset:192
	global_load_dwordx4 v[22:25], v[38:39], off
	global_load_dwordx4 v[30:33], v[38:39], off offset:64
	global_load_dwordx4 v[34:37], v[38:39], off offset:128
	global_load_dwordx4 v[38:41], v[38:39], off offset:192
	global_load_dwordx4 v[42:45], v[138:139], off
	global_load_dwordx4 v[50:53], v[138:139], off offset:64
	global_load_dwordx4 v[214:217], v[138:139], off offset:128
	global_load_dwordx4 v[218:221], v[138:139], off offset:192
	global_load_dwordx4 v[222:225], v[238:239], off
	global_load_dwordx4 v[226:229], v[238:239], off offset:64
	global_load_dwordx4 v[230:233], v[238:239], off offset:128
	global_load_dwordx4 v[234:237], v[238:239], off offset:192
	s_mov_b32 s19, 0x30000
	s_mov_b32 s96, 0x10000
	s_mov_b32 s24, 0x20000
	s_mov_b32 s0, s3
	s_waitcnt vmcnt(12)
	v_pk_fma_f32 v[6:7], v[146:147], v[104:105], v[6:7]
	v_pk_fma_f32 v[8:9], v[148:149], v[106:107], v[8:9]
	v_pk_fma_f32 v[10:11], v[150:151], v[108:109], v[10:11]
	v_pk_fma_f32 v[12:13], v[152:153], v[110:111], v[12:13]
	v_pk_fma_f32 v[14:15], v[154:155], v[130:131], v[14:15]
	v_pk_fma_f32 v[16:17], v[156:157], v[132:133], v[16:17]
	v_pk_fma_f32 v[18:19], v[158:159], v[26:27], v[18:19]
	v_pk_fma_f32 v[20:21], v[160:161], v[28:29], v[20:21]
	global_store_dwordx4 v[100:101], v[6:9], off
	global_store_dwordx4 v[100:101], v[10:13], off offset:64
	global_store_dwordx4 v[100:101], v[14:17], off offset:128
	global_store_dwordx4 v[100:101], v[18:21], off offset:192
	v_add_co_u32_e32 v240, vcc, 0x10000, v100
	s_nop 1
	v_addc_co_u32_e32 v241, vcc, 0, v101, vcc
	s_waitcnt vmcnt(12)
	v_pk_fma_f32 v[22:23], v[162:163], v[104:105], v[22:23]
	v_pk_fma_f32 v[24:25], v[164:165], v[106:107], v[24:25]
	v_pk_fma_f32 v[30:31], v[166:167], v[108:109], v[30:31]
	v_pk_fma_f32 v[32:33], v[168:169], v[110:111], v[32:33]
	v_pk_fma_f32 v[34:35], v[176:177], v[130:131], v[34:35]
	v_pk_fma_f32 v[36:37], v[178:179], v[132:133], v[36:37]
	v_pk_fma_f32 v[38:39], v[180:181], v[26:27], v[38:39]
	v_pk_fma_f32 v[40:41], v[182:183], v[28:29], v[40:41]
	global_store_dwordx4 v[240:241], v[22:25], off
	global_store_dwordx4 v[240:241], v[30:33], off offset:64
	global_store_dwordx4 v[240:241], v[34:37], off offset:128
	global_store_dwordx4 v[240:241], v[38:41], off offset:192
	v_add_co_u32_e32 v240, vcc, 0x20000, v100
	s_nop 1
	v_addc_co_u32_e32 v241, vcc, 0, v101, vcc
	s_waitcnt vmcnt(12)
	v_pk_fma_f32 v[42:43], v[184:185], v[104:105], v[42:43]
	v_pk_fma_f32 v[44:45], v[186:187], v[106:107], v[44:45]
	v_pk_fma_f32 v[50:51], v[210:211], v[108:109], v[50:51]
	v_pk_fma_f32 v[52:53], v[212:213], v[110:111], v[52:53]
	v_pk_fma_f32 v[214:215], v[58:59], v[130:131], v[214:215]
	v_pk_fma_f32 v[216:217], v[60:61], v[132:133], v[216:217]
	v_pk_fma_f32 v[218:219], v[66:67], v[26:27], v[218:219]
	v_pk_fma_f32 v[220:221], v[68:69], v[28:29], v[220:221]
	global_store_dwordx4 v[240:241], v[42:45], off
	global_store_dwordx4 v[240:241], v[50:53], off offset:64
	global_store_dwordx4 v[240:241], v[214:217], off offset:128
	global_store_dwordx4 v[240:241], v[218:221], off offset:192
	v_add_co_u32_e32 v240, vcc, 0x30000, v100
	s_nop 1
	v_addc_co_u32_e32 v241, vcc, 0, v101, vcc
	s_waitcnt vmcnt(12)
	v_pk_fma_f32 v[222:223], v[62:63], v[104:105], v[222:223]
	v_pk_fma_f32 v[224:225], v[64:65], v[106:107], v[224:225]
	v_pk_fma_f32 v[226:227], v[54:55], v[108:109], v[226:227]
	v_pk_fma_f32 v[228:229], v[56:57], v[110:111], v[228:229]
	v_pk_fma_f32 v[230:231], v[46:47], v[130:131], v[230:231]
	v_pk_fma_f32 v[232:233], v[48:49], v[132:133], v[232:233]
	v_pk_fma_f32 v[234:235], v[2:3], v[26:27], v[234:235]
	v_pk_fma_f32 v[236:237], v[4:5], v[28:29], v[236:237]
	s_and_b64 vcc, exec, s[34:35]
	global_store_dwordx4 v[240:241], v[222:225], off
	global_store_dwordx4 v[240:241], v[226:229], off offset:64
	global_store_dwordx4 v[240:241], v[230:233], off offset:128
	global_store_dwordx4 v[240:241], v[234:237], off offset:192
	s_cbranch_vccnz .LBB0_1061
